# PREP transposes: tile loads issued before the LDS-reuse barrier
# baseline (speedup 1.0000x reference)
; DI int otid() { int t = threadIdx.x; asm volatile("" : "+v"(t)); return t; }
; DI void transpose_tile(const float* __restrict__ src, u16* __restrict__ dst, int K, int N, int tk, int tn, int drow, float* tile) {
;   const int tid = otid();
;   __syncthreads();
; #pragma unroll
;   for (int i = 0; i < 4; ++i) {
;     int kr = (tid >> 4) + 16 * i, nc = (tid & 15) * 4;
;     float4 v = *(const float4*)(src + (size_t)(tk * 64 + kr) * N + tn * 64 + nc);
;     tile[kr * 65 + nc] = v.x; tile[kr * 65 + nc + 1] = v.y; tile[kr * 65 + nc + 2] = v.z; tile[kr * 65 + nc + 3] = v.w;
;   }
;   __syncthreads();
.LBB0_593:
	s_ashr_i32 s19, s13, 31
	s_mul_i32 s10, s15, s16
	s_mul_i32 s11, s10, s19
	s_mul_hi_u32 s20, s10, s13
	s_add_i32 s11, s20, s11
	s_mul_i32 s10, s10, s13
	s_lshl_b64 s[10:11], s[10:11], 2
	s_add_u32 s10, s0, s10
	s_addc_u32 s11, s1, s11
	s_mul_hi_u32 s0, s6, s13
	s_mul_i32 s1, s6, s19
	s_add_i32 s0, s0, s1
	s_mul_i32 s1, s7, s13
	s_add_i32 s1, s0, s1
	s_mul_i32 s0, s6, s13
	s_lshl_b64 s[0:1], s[0:1], 1
	s_add_u32 s8, s8, s0
	s_addc_u32 s9, s9, s1
	s_ashr_i32 s13, s12, 31
	v_mov_b32_e32 v1, v197
	s_lshl_b32 s0, s18, 6
	s_lshl_b64 s[6:7], s[12:13], 2
	s_add_u32 s6, s10, s6
	v_ashrrev_i32_e32 v8, 4, v1
	v_lshlrev_b32_e32 v2, 4, v1
	s_addc_u32 s7, s11, s7
	v_and_b32_e32 v198, 0xf0, v2
	v_add_u32_e32 v10, s0, v8
	v_lshl_add_u64 v[6:7], s[6:7], 0, v[198:199]
	v_mad_u64_u32 v[2:3], s[6:7], v10, s16, 0
	v_ashrrev_i32_e32 v5, 31, v10
	v_mov_b32_e32 v4, v3
	v_mad_u64_u32 v[4:5], s[6:7], v5, s16, v[4:5]
	v_mov_b32_e32 v3, v4
	v_lshl_add_u64 v[2:3], v[2:3], 2, v[6:7]
	global_load_dwordx4 v[2:5], v[2:3], off
	v_add_u32_e32 v32, 16, v10
	v_ashrrev_i32_e32 v35, 31, v32
	v_mad_u64_u32 v[32:33], s[6:7], v32, s16, 0
	v_mov_b32_e32 v34, v33
	v_mad_u64_u32 v[34:35], s[6:7], v35, s16, v[34:35]
	v_mov_b32_e32 v33, v34
	v_lshl_add_u64 v[32:33], v[32:33], 2, v[6:7]
	global_load_dwordx4 v[48:51], v[32:33], off
	v_add_u32_e32 v36, 32, v10
	v_ashrrev_i32_e32 v39, 31, v36
	v_mad_u64_u32 v[36:37], s[6:7], v36, s16, 0
	v_mov_b32_e32 v38, v37
	v_mad_u64_u32 v[38:39], s[6:7], v39, s16, v[38:39]
	v_mov_b32_e32 v37, v38
	v_lshl_add_u64 v[36:37], v[36:37], 2, v[6:7]
	global_load_dwordx4 v[68:71], v[36:37], off
	v_add_u32_e32 v44, 48, v10
	v_ashrrev_i32_e32 v47, 31, v44
	v_mad_u64_u32 v[44:45], s[6:7], v44, s16, 0
	v_mov_b32_e32 v46, v45
	v_mad_u64_u32 v[46:47], s[6:7], v47, s16, v[46:47]
	v_mov_b32_e32 v45, v46
	v_lshl_add_u64 v[44:45], v[44:45], 2, v[6:7]
	global_load_dwordx4 v[72:75], v[44:45], off
	s_movk_i32 s1, 0x104
	v_mad_u64_u32 v[8:9], s[6:7], v8, s1, v[198:199]
	v_add_u32_e32 v9, 0x1040, v8
	v_ashrrev_i32_e32 v24, 3, v1
	v_lshlrev_b32_e32 v1, 3, v1
	v_and_b32_e32 v1, 56, v1
	s_ashr_i32 s1, s0, 31
	v_lshlrev_b32_e32 v198, 1, v1
	v_mul_u32_u24_e32 v1, 0x104, v1
	s_lshl_b64 s[0:1], s[0:1], 1
	v_lshl_add_u32 v1, v24, 2, v1
	s_add_u32 s0, s8, s0
	s_addc_u32 s1, s9, s1
	s_add_i32 s14, s14, s37
	s_cmpk_gt_i32 s14, 0x23cf
	s_waitcnt lgkmcnt(0)
	s_barrier
	s_waitcnt vmcnt(3)
	ds_write2_b32 v8, v2, v3 offset1:1
	ds_write2_b32 v8, v4, v5 offset0:2 offset1:3
	s_waitcnt vmcnt(2)
	ds_write2_b32 v9, v48, v49 offset1:1
	v_add_u32_e32 v2, 0x1048, v8
	ds_write2_b32 v2, v50, v51 offset1:1
	v_add_u32_e32 v9, 0x2080, v8
	s_waitcnt vmcnt(1)
	ds_write2_b32 v9, v68, v69 offset1:1
	v_add_u32_e32 v2, 0x2088, v8
	ds_write2_b32 v2, v70, v71 offset1:1
	v_add_u32_e32 v6, 0x30c0, v8
	s_waitcnt vmcnt(0)
	ds_write2_b32 v6, v72, v73 offset1:1
	v_add_u32_e32 v2, 0x30c8, v8
	ds_write2_b32 v2, v74, v75 offset1:1
	s_waitcnt lgkmcnt(0)
	s_barrier
	ds_read2_b32 v[8:9], v1 offset1:32
	ds_read2_b32 v[10:11], v1 offset0:65 offset1:97
	ds_read2_b32 v[12:13], v1 offset0:130 offset1:162
	ds_read2_b32 v[14:15], v1 offset0:195 offset1:227
	v_add_u32_e32 v1, 0x400, v1
	ds_read2_b32 v[16:17], v1 offset0:4 offset1:36
	ds_read2_b32 v[18:19], v1 offset0:69 offset1:101
	ds_read2_b32 v[20:21], v1 offset0:134 offset1:166
	ds_read2_b32 v[22:23], v1 offset0:199 offset1:231
	v_add_u32_e32 v1, s17, v24
	v_lshl_add_u64 v[6:7], s[0:1], 0, v[198:199]
	v_mad_u64_u32 v[24:25], s[0:1], v1, s15, 0
	s_waitcnt lgkmcnt(6)
	v_cvt_pk_bf16_f32 v2, v8, v10
	v_ashrrev_i32_e32 v10, 31, v1
	v_mov_b32_e32 v8, v25
	v_mad_u64_u32 v[26:27], s[0:1], v10, s15, v[8:9]
	v_mov_b32_e32 v25, v26
	s_waitcnt lgkmcnt(4)
	v_cvt_pk_bf16_f32 v3, v12, v14
	s_waitcnt lgkmcnt(2)
	v_cvt_pk_bf16_f32 v4, v16, v18
	s_waitcnt lgkmcnt(0)
	v_cvt_pk_bf16_f32 v5, v20, v22
	v_lshl_add_u64 v[24:25], v[24:25], 1, v[6:7]
	v_add_u32_e32 v1, 32, v1
	global_store_dwordx4 v[24:25], v[2:5], off
	s_nop 1
	v_cvt_pk_bf16_f32 v2, v9, v11
	v_mad_u64_u32 v[8:9], s[0:1], v1, s15, 0
	v_ashrrev_i32_e32 v11, 31, v1
	v_mov_b32_e32 v10, v9
	v_mad_u64_u32 v[10:11], s[0:1], v11, s15, v[10:11]
	v_mov_b32_e32 v9, v10
	v_cvt_pk_bf16_f32 v3, v13, v15
	v_cvt_pk_bf16_f32 v4, v17, v19
	v_cvt_pk_bf16_f32 v5, v21, v23
	v_lshl_add_u64 v[6:7], v[8:9], 1, v[6:7]
	global_store_dwordx4 v[6:7], v[2:5], off
	s_cbranch_scc1 .LBB0_577
